# ssd_chunk_unit stage_raw: row loads issued together, one wait per LDS write (on top of hand-scheduled ssd_y_unit)
# speedup vs baseline: 1.0135x; 1.0050x over previous
;     DEVI bf16_t* proj() const { return (bf16_t*)(ws + WS_PROJ); }
; DEVI unsigned pk2bf(float lo, float hi) { unsigned r; asm volatile("v_cvt_pk_bf16_f32 %0, %1, %2" : "=v"(r) : "v"(lo), "v"(hi)); return r; }
; #define LAS __attribute__((address_space(3)))
; template <int NC16> DEVI void stage_raw(const bf16_t* proj, int r0, int col0, const float* hist, int hcol0, bool first_chunk, LAS unsigned char* rawb, int lane) {
;     constexpr int RPI = 64 / NC16;
; #pragma unroll
;     for (int i = 0; i * RPI < 67; ++i) {
;         const int row = i * RPI + lane / NC16, pc = lane % NC16;
;         if (row < 67) { const int s = row - 3; u32x4_t v = {0u, 0u, 0u, 0u};
;             if (s >= 0 || !first_chunk) v = *(const u32x4_t*)(proj + (size_t)(r0 + s) * NP + col0 + pc * 8);
;             else if (hist) { const float* hp = hist + (3 + s) * CONVC + hcol0 + pc * 8; v = (u32x4_t){pk2bf(hp[0], hp[1]), pk2bf(hp[2], hp[3]), pk2bf(hp[4], hp[5]), pk2bf(hp[6], hp[7])}; }
;             *(LAS u32x4_t*)(rawb + row * 128 + pc * 16) = v; }
;     }
; }
; DEVI void ssd_chunk_unit(const P& p, int l, int ci, LAS unsigned char* lds, int tid, int wave, int lane) {
;     ...
;         stage_raw<4>(p.proj(), r0, O_XBC + 512 + 32 * wave, hist, 512 + 32 * wave, first_chunk, rawb, lane);
.LBB0_255:
	s_or_b64 exec, exec, s[86:87]
	v_add_u32_e32 v6, s3, v174
	v_mad_i64_i32 v[6:7], s[84:85], v6, s88, v[112:113]
	global_load_dwordx4 v[8:11], v[6:7], off
	v_add_u32_e32 v6, s3, v175
	v_mad_i64_i32 v[6:7], s[84:85], v6, s88, v[112:113]
	global_load_dwordx4 v[12:15], v[6:7], off
	v_add_u32_e32 v6, s3, v177
	v_mad_i64_i32 v[6:7], s[84:85], v6, s88, v[112:113]
	global_load_dwordx4 v[16:19], v[6:7], off
	v_add_u32_e32 v6, s3, v178
	v_mad_i64_i32 v[6:7], s[84:85], v6, s88, v[112:113]
	s_mov_b64 s[84:85], exec
	v_readlane_b32 s86, v253, 56
	v_readlane_b32 s87, v253, 57
	s_and_b64 s[86:87], s[84:85], s[86:87]
	s_mov_b64 exec, s[86:87]
	global_load_dwordx4 v[20:23], v[6:7], off
	s_mov_b64 exec, s[84:85]
	s_waitcnt vmcnt(4)
	ds_write_b128 v202, v[2:5] offset:56320
	s_waitcnt vmcnt(3)
	ds_write_b128 v203, v[8:11] offset:56320
	s_waitcnt vmcnt(2)
	ds_write_b128 v204, v[12:15] offset:56320
	s_waitcnt vmcnt(1)
	ds_write_b128 v205, v[16:19] offset:56320
	s_waitcnt vmcnt(0)
	s_mov_b64 exec, s[86:87]
	ds_write_b128 v206, v[20:23] offset:56320

;     DEVI bf16_t* proj() const { return (bf16_t*)(ws + WS_PROJ); }
; DEVI unsigned pk2bf(float lo, float hi) { unsigned r; asm volatile("v_cvt_pk_bf16_f32 %0, %1, %2" : "=v"(r) : "v"(lo), "v"(hi)); return r; }
; #define LAS __attribute__((address_space(3)))
; template <int NC16> DEVI void stage_raw(const bf16_t* proj, int r0, int col0, const float* hist, int hcol0, bool first_chunk, LAS unsigned char* rawb, int lane) {
;     constexpr int RPI = 64 / NC16;
; #pragma unroll
;     for (int i = 0; i * RPI < 67; ++i) {
;         const int row = i * RPI + lane / NC16, pc = lane % NC16;
;         if (row < 67) { const int s = row - 3; u32x4_t v = {0u, 0u, 0u, 0u};
;             if (s >= 0 || !first_chunk) v = *(const u32x4_t*)(proj + (size_t)(r0 + s) * NP + col0 + pc * 8);
;             else if (hist) { const float* hp = hist + (3 + s) * CONVC + hcol0 + pc * 8; v = (u32x4_t){pk2bf(hp[0], hp[1]), pk2bf(hp[2], hp[3]), pk2bf(hp[4], hp[5]), pk2bf(hp[6], hp[7])}; }
;             *(LAS u32x4_t*)(rawb + row * 128 + pc * 16) = v; }
;     }
; }
; DEVI void ssd_chunk_unit(const P& p, int l, int ci, LAS unsigned char* lds, int tid, int wave, int lane) {
;     ...
;     stage_raw<8>(p.proj(), r0, O_XBC + 64 * wave, hist, 64 * wave, first_chunk, lds + SSD_RAW + wave * SSD_RAWW, lane);
.LBB0_261:
	s_or_b64 exec, exec, s[80:81]
	v_add_u32_e32 v44, s3, v181
	v_mad_i64_i32 v[44:45], s[80:81], v44, s88, v[114:115]
	global_load_dwordx4 v[12:15], v[44:45], off
	v_add_u32_e32 v44, s3, v182
	v_mad_i64_i32 v[44:45], s[80:81], v44, s88, v[114:115]
	global_load_dwordx4 v[16:19], v[44:45], off
	v_add_u32_e32 v44, s3, v183
	v_mad_i64_i32 v[44:45], s[80:81], v44, s88, v[114:115]
	global_load_dwordx4 v[20:23], v[44:45], off
	v_add_u32_e32 v44, s3, v184
	v_mad_i64_i32 v[44:45], s[80:81], v44, s88, v[114:115]
	global_load_dwordx4 v[24:27], v[44:45], off
	v_add_u32_e32 v44, s3, v185
	v_mad_i64_i32 v[44:45], s[80:81], v44, s88, v[114:115]
	global_load_dwordx4 v[28:31], v[44:45], off
	v_add_u32_e32 v44, s3, v186
	v_mad_i64_i32 v[44:45], s[80:81], v44, s88, v[114:115]
	global_load_dwordx4 v[32:35], v[44:45], off
	v_add_u32_e32 v44, s3, v187
	v_mad_i64_i32 v[44:45], s[80:81], v44, s88, v[114:115]
	global_load_dwordx4 v[36:39], v[44:45], off
	v_add_u32_e32 v44, s3, v188
	v_mad_i64_i32 v[44:45], s[80:81], v44, s88, v[114:115]
	s_mov_b64 s[80:81], exec
	v_readlane_b32 s82, v253, 62
	v_readlane_b32 s83, v253, 63
	s_and_b64 s[82:83], s[80:81], s[82:83]
	s_mov_b64 exec, s[82:83]
	global_load_dwordx4 v[40:43], v[44:45], off
	s_mov_b64 exec, s[80:81]
	s_waitcnt vmcnt(8)
	ds_write_b128 v234, v[2:5] offset:56320
	s_waitcnt vmcnt(7)
	ds_write_b128 v235, v[12:15] offset:56320
	s_waitcnt vmcnt(6)
	ds_write_b128 v236, v[16:19] offset:56320
	s_waitcnt vmcnt(5)
	ds_write_b128 v237, v[20:23] offset:56320
	s_waitcnt vmcnt(4)
	ds_write_b128 v238, v[24:27] offset:56320
	s_waitcnt vmcnt(3)
	ds_write_b128 v239, v[28:31] offset:56320
	s_waitcnt vmcnt(2)
	ds_write_b128 v240, v[32:35] offset:56320
	s_waitcnt vmcnt(1)
	ds_write_b128 v241, v[36:39] offset:56320
	s_waitcnt vmcnt(0)
	s_mov_b64 exec, s[82:83]
	ds_write_b128 v242, v[40:43] offset:56320
